# attention: static prio 1 for waves 4-7, Q loads not drained before first stage barrier, rescale test trimmed, redundant vmcnt(0) before V reads removed
# speedup vs baseline: 1.0701x; 1.0152x over previous
.LBB0_535:
	s_setprio 0
	s_add_i32 s57, s57, s34
	s_add_i32 s56, s56, s34
	s_add_i32 s2, s2, s40
	s_cmpk_gt_i32 s57, 0x27f
	s_cbranch_scc1 .LBB0_605

.LBB0_557:
	v_cmp_lt_u32_e32 vcc, 255, v194
	s_cbranch_vccz .Lsp_skip
	s_setprio 1
.Lsp_skip:
	s_and_b64 s[6:7], s[50:51], exec
	s_cselect_b32 s8, s31, s30
	s_cselect_b32 s10, s29, s28
	s_and_b64 s[6:7], s[90:91], exec
	s_cselect_b32 s10, s8, s10
	s_lshl_b32 s79, s10, 7
	v_or_b32_e32 v1, s79, v159
	v_add_u32_e32 v1, s60, v1
	v_mad_u64_u32 v[2:3], s[6:7], v1, s33, v[144:145]
	v_readfirstlane_b32 s6, v160
	s_mov_b32 m0, s6
	v_readfirstlane_b32 s6, v161
	global_load_dwordx4 v[128:131], v[2:3], off
	global_load_dwordx4 v[132:135], v[2:3], off offset:32
	global_load_dwordx4 v[136:139], v[2:3], off offset:64
	global_load_dwordx4 v[140:143], v[2:3], off offset:96
	s_waitcnt lgkmcnt(0)
	s_barrier
	buffer_load_dwordx4 v162, s[44:47], s36 offen lds
	s_mov_b32 m0, s6
	v_readfirstlane_b32 s6, v164
	buffer_load_dwordx4 v162, s[44:47], s37 offen lds
	s_mov_b32 m0, s6
	v_readfirstlane_b32 s6, v165
	buffer_load_dwordx4 v163, s[44:47], s36 offen lds
	s_mov_b32 m0, s6
	s_lshl_b32 s8, s10, 1
	buffer_load_dwordx4 v163, s[44:47], s37 offen lds
	s_waitcnt vmcnt(0)
	s_cmp_lt_u32 s10, 2
	s_waitcnt vmcnt(0)
	s_barrier
	s_cbranch_scc1 .LBB0_566
	v_mov_b32_e32 v14, v0
	v_mov_b32_e32 v15, v0
	s_max_i32 s6, s8, 3
	v_mov_b32_e32 v1, v0
	v_mov_b32_e32 v2, v0
	v_mov_b32_e32 v3, v0
	v_mov_b32_e32 v4, v0
	v_mov_b32_e32 v5, v0
	v_mov_b32_e32 v6, v0
	v_mov_b32_e32 v7, v0
	v_mov_b32_e32 v8, v0
	v_mov_b32_e32 v9, v0
	v_mov_b32_e32 v10, v0
	v_mov_b32_e32 v11, v0
	v_mov_b32_e32 v12, v0
	v_mov_b32_e32 v13, v0
	v_mov_b64_e32 v[30:31], v[14:15]
	v_mov_b64_e32 v[46:47], v[14:15]
	v_mov_b64_e32 v[62:63], v[14:15]
	v_mov_b64_e32 v[78:79], v[14:15]
	s_add_i32 s11, s6, -2
	s_mov_b32 s64, 0
	v_mov_b32_e32 v147, 0
	s_mov_b32 s13, s27
	v_mov_b64_e32 v[28:29], v[12:13]
	v_mov_b64_e32 v[26:27], v[10:11]
	v_mov_b64_e32 v[24:25], v[8:9]
	v_mov_b64_e32 v[22:23], v[6:7]
	v_mov_b64_e32 v[20:21], v[4:5]
	v_mov_b64_e32 v[18:19], v[2:3]
	v_mov_b64_e32 v[16:17], v[0:1]
	v_mov_b64_e32 v[44:45], v[12:13]
	v_mov_b64_e32 v[42:43], v[10:11]
	v_mov_b64_e32 v[40:41], v[8:9]
	v_mov_b64_e32 v[38:39], v[6:7]
	v_mov_b64_e32 v[36:37], v[4:5]
	v_mov_b64_e32 v[34:35], v[2:3]
	v_mov_b64_e32 v[32:33], v[0:1]
	v_mov_b64_e32 v[60:61], v[12:13]
	v_mov_b64_e32 v[58:59], v[10:11]
	v_mov_b64_e32 v[56:57], v[8:9]
	v_mov_b64_e32 v[54:55], v[6:7]
	v_mov_b64_e32 v[52:53], v[4:5]
	v_mov_b64_e32 v[50:51], v[2:3]
	v_mov_b64_e32 v[48:49], v[0:1]
	v_mov_b64_e32 v[76:77], v[12:13]
	v_mov_b64_e32 v[74:75], v[10:11]
	v_mov_b64_e32 v[72:73], v[8:9]
	v_mov_b64_e32 v[70:71], v[6:7]
	v_mov_b64_e32 v[68:69], v[4:5]
	v_mov_b64_e32 v[66:67], v[2:3]
	v_mov_b64_e32 v[64:65], v[0:1]
	s_mov_b32 s65, 0
	v_mov_b32_e32 v174, 0
	v_mov_b32_e32 v80, v151
	v_mov_b32_e32 v81, v151
	v_mov_b32_e32 v82, v151
	v_mov_b32_e32 v83, v151
	v_mov_b32_e32 v84, v151
	v_mov_b32_e32 v85, v151
	v_mov_b32_e32 v86, v151
	v_mov_b32_e32 v87, v151
	v_mov_b32_e32 v88, v151
	v_mov_b32_e32 v89, v151
	v_mov_b32_e32 v90, v151
	v_mov_b32_e32 v91, v151
	v_mov_b32_e32 v92, v151
	v_mov_b32_e32 v93, v151
	v_mov_b32_e32 v94, v151
	v_mov_b32_e32 v95, v151
	s_branch .LBB0_561

.LBB0_560:
	v_add_u32_e32 v1, s98, v156
	v_cvt_pk_bf16_f32 v2, v96, v97
	v_cvt_pk_bf16_f32 v4, v100, v101
	v_cvt_pk_bf16_f32 v5, v102, v103
	v_cvt_pk_bf16_f32 v10, v104, v105
	v_cvt_pk_bf16_f32 v11, v106, v107
	v_cvt_pk_bf16_f32 v12, v108, v109
	v_cvt_pk_bf16_f32 v13, v110, v111
	v_cvt_pk_bf16_f32 v96, v112, v113
	v_cvt_pk_bf16_f32 v97, v114, v115
	v_add_u32_e32 v14, s98, v157
	ds_read_b64_tr_b16 v[100:101], v1 offset:16384
	ds_read_b64_tr_b16 v[102:103], v14 offset:18432
	ds_read_b64_tr_b16 v[104:105], v1 offset:20480
	ds_read_b64_tr_b16 v[106:107], v14 offset:22528
	ds_read_b64_tr_b16 v[108:109], v1 offset:24576
	ds_read_b64_tr_b16 v[110:111], v14 offset:26624
	ds_read_b64_tr_b16 v[112:113], v1 offset:28672
	ds_read_b64_tr_b16 v[114:115], v14 offset:30720
	s_add_i32 s65, s65, 1
	v_add_f32_e32 v174, v174, v146
	v_cvt_pk_bf16_f32 v3, v98, v99
	v_cvt_pk_bf16_f32 v98, v116, v117
	v_cvt_pk_bf16_f32 v99, v118, v119
	v_cvt_pk_bf16_f32 v6, v120, v121
	v_cvt_pk_bf16_f32 v7, v122, v123
	v_cvt_pk_bf16_f32 v8, v124, v125
	v_cvt_pk_bf16_f32 v9, v126, v127
	s_waitcnt lgkmcnt(6)
	v_mfma_f32_32x32x16_bf16 v[64:79], v[100:103], v[2:5], v[64:79]
	v_add_u32_e32 v1, s98, v166
	v_add_u32_e32 v14, s98, v167
	s_waitcnt lgkmcnt(4)
	v_mfma_f32_32x32x16_bf16 v[64:79], v[104:107], v[10:13], v[64:79]
	s_waitcnt lgkmcnt(2)
	v_mfma_f32_32x32x16_bf16 v[64:79], v[108:111], v[96:99], v[64:79]
	s_waitcnt lgkmcnt(0)
	v_mfma_f32_32x32x16_bf16 v[64:79], v[112:115], v[6:9], v[64:79]
	ds_read_b64_tr_b16 v[100:101], v1 offset:16384
	ds_read_b64_tr_b16 v[102:103], v14 offset:16384
	ds_read_b64_tr_b16 v[104:105], v1 offset:20480
	ds_read_b64_tr_b16 v[106:107], v14 offset:20480
	ds_read_b64_tr_b16 v[108:109], v1 offset:24576
	ds_read_b64_tr_b16 v[110:111], v14 offset:24576
	ds_read_b64_tr_b16 v[112:113], v1 offset:28672
	ds_read_b64_tr_b16 v[114:115], v14 offset:28672
	s_waitcnt lgkmcnt(6)
	v_mfma_f32_32x32x16_bf16 v[48:63], v[100:103], v[2:5], v[48:63]
	v_add_u32_e32 v1, s98, v168
	v_add_u32_e32 v14, s98, v169
	s_waitcnt lgkmcnt(4)
	v_mfma_f32_32x32x16_bf16 v[48:63], v[104:107], v[10:13], v[48:63]
	s_waitcnt lgkmcnt(2)
	v_mfma_f32_32x32x16_bf16 v[48:63], v[108:111], v[96:99], v[48:63]
	s_waitcnt lgkmcnt(0)
	v_mfma_f32_32x32x16_bf16 v[48:63], v[112:115], v[6:9], v[48:63]
	ds_read_b64_tr_b16 v[100:101], v1 offset:16384
	ds_read_b64_tr_b16 v[102:103], v14 offset:16384
	ds_read_b64_tr_b16 v[104:105], v1 offset:20480
	ds_read_b64_tr_b16 v[106:107], v14 offset:20480
	ds_read_b64_tr_b16 v[108:109], v1 offset:24576
	ds_read_b64_tr_b16 v[110:111], v14 offset:24576
	ds_read_b64_tr_b16 v[112:113], v1 offset:28672
	ds_read_b64_tr_b16 v[114:115], v14 offset:28672
	s_waitcnt lgkmcnt(6)
	v_mfma_f32_32x32x16_bf16 v[32:47], v[100:103], v[2:5], v[32:47]
	v_add_u32_e32 v1, s98, v170
	v_add_u32_e32 v14, s98, v171
	s_waitcnt lgkmcnt(4)
	v_mfma_f32_32x32x16_bf16 v[32:47], v[104:107], v[10:13], v[32:47]
	s_waitcnt lgkmcnt(2)
	v_mfma_f32_32x32x16_bf16 v[32:47], v[108:111], v[96:99], v[32:47]
	s_waitcnt lgkmcnt(0)
	v_mfma_f32_32x32x16_bf16 v[32:47], v[112:115], v[6:9], v[32:47]
	ds_read_b64_tr_b16 v[100:101], v1 offset:16384
	ds_read_b64_tr_b16 v[102:103], v14 offset:16384
	ds_read_b64_tr_b16 v[104:105], v1 offset:20480
	ds_read_b64_tr_b16 v[106:107], v14 offset:20480
	ds_read_b64_tr_b16 v[108:109], v1 offset:24576
	ds_read_b64_tr_b16 v[110:111], v14 offset:24576
	ds_read_b64_tr_b16 v[112:113], v1 offset:28672
	ds_read_b64_tr_b16 v[114:115], v14 offset:28672
	s_waitcnt lgkmcnt(6)
	v_mfma_f32_32x32x16_bf16 v[16:31], v[100:103], v[2:5], v[16:31]
	s_waitcnt vmcnt(0)
	s_add_i32 s13, s13, 0xc0000
	s_cmp_eq_u32 s11, s65
	s_waitcnt lgkmcnt(0)
	s_barrier
	v_mfma_f32_32x32x16_bf16 v[16:31], v[104:107], v[10:13], v[16:31]
	v_mfma_f32_32x32x16_bf16 v[16:31], v[108:111], v[96:99], v[16:31]
	v_mfma_f32_32x32x16_bf16 v[16:31], v[112:115], v[6:9], v[16:31]
	s_cbranch_scc1 .LBB0_567
.LBB0_561:
	s_mov_b32 s6, s64
	s_add_i32 s64, s64, 0x8000
	s_and_b32 s7, s64, 0x8000
	v_add_u32_e32 v1, s7, v160
	v_add_u32_e32 v2, 0x4000, v1
	v_readfirstlane_b32 s54, v1
	s_mov_b32 m0, s54
	v_readfirstlane_b32 s54, v2
	v_add_u32_e32 v2, 0x400, v1
	s_add_i32 s7, s13, 0x800
	buffer_load_dwordx4 v162, s[44:47], s13 offen lds
	s_mov_b32 m0, s54
	v_readfirstlane_b32 s54, v2
	v_add_u32_e32 v1, 0x4400, v1
	buffer_load_dwordx4 v162, s[44:47], s7 offen lds
	s_mov_b32 m0, s54
	v_readfirstlane_b32 s54, v1
	buffer_load_dwordx4 v163, s[44:47], s13 offen lds
	s_mov_b32 m0, s54
	s_and_b32 s98, s6, 0x8000
	buffer_load_dwordx4 v163, s[44:47], s7 offen lds
	v_add_u32_e32 v1, s98, v152
	v_add_u32_e32 v2, s98, v153
	v_add_u32_e32 v3, s98, v154
	v_add_u32_e32 v4, s98, v155
	ds_read_b128 v[6:9], v1
	ds_read_b128 v[10:13], v1 offset:8192
	ds_read_b128 v[176:179], v2
	ds_read_b128 v[180:183], v2 offset:8192
	ds_read_b128 v[184:187], v3
	ds_read_b128 v[188:191], v3 offset:8192
	ds_read_b128 v[204:207], v4
	ds_read_b128 v[208:211], v4 offset:8192
	s_cmp_eq_u32 s65, 0
	s_cselect_b64 s[6:7], -1, 0
	s_cmp_lg_u32 s65, 0
	s_cselect_b64 s[54:55], -1, 0
	s_waitcnt lgkmcnt(7)
	v_mfma_f32_32x32x16_bf16 v[96:111], v[6:9], v[128:131], v[80:95]
	s_and_b64 vcc, exec, s[6:7]
	s_waitcnt lgkmcnt(6)
	v_mfma_f32_32x32x16_bf16 v[112:127], v[10:13], v[128:131], v[80:95]
	s_waitcnt lgkmcnt(5)
	v_mfma_f32_32x32x16_bf16 v[96:111], v[176:179], v[132:135], v[96:111]
	s_waitcnt lgkmcnt(4)
	v_mfma_f32_32x32x16_bf16 v[112:127], v[180:183], v[132:135], v[112:127]
	s_waitcnt lgkmcnt(3)
	v_mfma_f32_32x32x16_bf16 v[96:111], v[184:187], v[136:139], v[96:111]
	s_waitcnt lgkmcnt(2)
	v_mfma_f32_32x32x16_bf16 v[112:127], v[188:191], v[136:139], v[112:127]
	s_waitcnt lgkmcnt(1)
	v_mfma_f32_32x32x16_bf16 v[96:111], v[204:207], v[140:143], v[96:111]
	s_waitcnt lgkmcnt(0)
	v_mfma_f32_32x32x16_bf16 v[112:127], v[208:211], v[140:143], v[112:127]
	s_cbranch_vccnz .LBB0_563
	s_nop 8
	v_exp_f32_e32 v96, v96
	s_nop 0
	v_exp_f32_e32 v112, v112
	v_exp_f32_e32 v97, v97
	v_exp_f32_e32 v113, v113
	v_add_f32_e32 v5, 0, v96
	v_exp_f32_e32 v98, v98
	v_add_f32_e32 v5, v112, v5
	v_exp_f32_e32 v114, v114
	v_add_f32_e32 v5, v97, v5
	v_exp_f32_e32 v99, v99
	v_add_f32_e32 v5, v113, v5
	v_exp_f32_e32 v115, v115
	v_add_f32_e32 v5, v98, v5
	v_exp_f32_e32 v100, v100
	v_add_f32_e32 v5, v114, v5
	v_exp_f32_e32 v116, v116
	v_add_f32_e32 v5, v99, v5
	v_exp_f32_e32 v101, v101
	v_add_f32_e32 v5, v115, v5
	v_exp_f32_e32 v117, v117
	v_add_f32_e32 v5, v100, v5
	v_exp_f32_e32 v102, v102
	v_add_f32_e32 v5, v116, v5
	v_exp_f32_e32 v118, v118
	v_add_f32_e32 v5, v101, v5
	v_exp_f32_e32 v103, v103
	v_add_f32_e32 v5, v117, v5
	v_exp_f32_e32 v119, v119
	v_add_f32_e32 v5, v102, v5
	v_exp_f32_e32 v104, v104
	v_add_f32_e32 v5, v118, v5
	v_exp_f32_e32 v120, v120
	v_add_f32_e32 v5, v103, v5
	v_exp_f32_e32 v105, v105
	v_add_f32_e32 v5, v119, v5
	v_exp_f32_e32 v121, v121
	v_add_f32_e32 v5, v104, v5
	v_exp_f32_e32 v106, v106
	v_add_f32_e32 v5, v120, v5
	v_exp_f32_e32 v122, v122
	v_add_f32_e32 v5, v105, v5
	v_exp_f32_e32 v107, v107
	v_add_f32_e32 v5, v121, v5
	v_exp_f32_e32 v123, v123
	v_add_f32_e32 v5, v106, v5
	v_exp_f32_e32 v108, v108
	v_add_f32_e32 v5, v122, v5
	v_exp_f32_e32 v124, v124
	v_add_f32_e32 v5, v107, v5
	v_exp_f32_e32 v109, v109
	v_add_f32_e32 v5, v123, v5
	v_exp_f32_e32 v125, v125
	v_add_f32_e32 v5, v108, v5
	v_exp_f32_e32 v110, v110
	v_add_f32_e32 v5, v124, v5
	v_exp_f32_e32 v126, v126
	v_add_f32_e32 v5, v109, v5
	v_exp_f32_e32 v111, v111
	v_add_f32_e32 v5, v125, v5
	v_exp_f32_e32 v127, v127
	v_add_f32_e32 v5, v110, v5
	v_add_f32_e32 v5, v126, v5
	v_add_f32_e32 v5, v111, v5
	v_add_f32_e32 v146, v127, v5
	v_cmp_nge_f32_e32 vcc, s26, v146
	s_cmp_lg_u64 vcc, 0
	s_cbranch_scc0 .LBB0_560
	s_branch .LBB0_564

.LBB0_570:
	v_cvt_pk_bf16_f32 v10, v10, v11
	v_cvt_pk_bf16_f32 v11, v12, v13
	v_cvt_pk_bf16_f32 v12, v14, v15
	v_add_u32_e32 v14, s64, v156
	v_cvt_pk_bf16_f32 v2, v2, v3
	v_cvt_pk_bf16_f32 v3, v4, v5
	v_cvt_pk_bf16_f32 v4, v6, v7
	v_cvt_pk_bf16_f32 v6, v112, v113
	v_cvt_pk_bf16_f32 v7, v114, v115
	v_cvt_pk_bf16_f32 v13, v96, v97
	v_cvt_pk_bf16_f32 v96, v98, v99
	v_cvt_pk_bf16_f32 v97, v100, v101
	v_cvt_pk_bf16_f32 v98, v102, v103
	v_cvt_pk_bf16_f32 v99, v104, v105
	v_add_u32_e32 v15, s64, v157
	ds_read_b64_tr_b16 v[100:101], v14 offset:16384
	ds_read_b64_tr_b16 v[102:103], v15 offset:18432
	ds_read_b64_tr_b16 v[104:105], v14 offset:20480
	ds_read_b64_tr_b16 v[106:107], v15 offset:22528
	ds_read_b64_tr_b16 v[108:109], v14 offset:24576
	ds_read_b64_tr_b16 v[110:111], v15 offset:26624
	ds_read_b64_tr_b16 v[112:113], v14 offset:28672
	ds_read_b64_tr_b16 v[114:115], v15 offset:30720
	v_add_f32_e32 v174, v174, v146
	v_cvt_pk_bf16_f32 v5, v8, v9
	v_cvt_pk_bf16_f32 v8, v116, v117
	v_cvt_pk_bf16_f32 v9, v118, v119
	s_waitcnt lgkmcnt(6)
	v_mfma_f32_32x32x16_bf16 v[64:79], v[100:103], v[2:5], v[64:79]
	v_add_u32_e32 v14, s64, v166
	v_add_u32_e32 v15, s64, v167
	s_waitcnt lgkmcnt(4)
	v_mfma_f32_32x32x16_bf16 v[64:79], v[104:107], v[6:9], v[64:79]
	s_waitcnt lgkmcnt(2)
	v_mfma_f32_32x32x16_bf16 v[64:79], v[108:111], v[10:13], v[64:79]
	s_waitcnt lgkmcnt(0)
	v_mfma_f32_32x32x16_bf16 v[64:79], v[112:115], v[96:99], v[64:79]
	ds_read_b64_tr_b16 v[100:101], v14 offset:16384
	ds_read_b64_tr_b16 v[102:103], v15 offset:16384
	ds_read_b64_tr_b16 v[104:105], v14 offset:20480
	ds_read_b64_tr_b16 v[106:107], v15 offset:20480
	ds_read_b64_tr_b16 v[108:109], v14 offset:24576
	ds_read_b64_tr_b16 v[110:111], v15 offset:24576
	ds_read_b64_tr_b16 v[112:113], v14 offset:28672
	ds_read_b64_tr_b16 v[114:115], v15 offset:28672
	s_waitcnt lgkmcnt(6)
	v_mfma_f32_32x32x16_bf16 v[48:63], v[100:103], v[2:5], v[48:63]
	v_add_u32_e32 v14, s64, v168
	v_add_u32_e32 v15, s64, v169
	s_waitcnt lgkmcnt(4)
	v_mfma_f32_32x32x16_bf16 v[48:63], v[104:107], v[6:9], v[48:63]
	s_waitcnt lgkmcnt(2)
	v_mfma_f32_32x32x16_bf16 v[48:63], v[108:111], v[10:13], v[48:63]
	s_waitcnt lgkmcnt(0)
	v_mfma_f32_32x32x16_bf16 v[48:63], v[112:115], v[96:99], v[48:63]
	ds_read_b64_tr_b16 v[100:101], v14 offset:16384
	ds_read_b64_tr_b16 v[102:103], v15 offset:16384
	ds_read_b64_tr_b16 v[104:105], v14 offset:20480
	ds_read_b64_tr_b16 v[106:107], v15 offset:20480
	ds_read_b64_tr_b16 v[108:109], v14 offset:24576
	ds_read_b64_tr_b16 v[110:111], v15 offset:24576
	ds_read_b64_tr_b16 v[112:113], v14 offset:28672
	ds_read_b64_tr_b16 v[114:115], v15 offset:28672
	s_waitcnt lgkmcnt(6)
	v_mfma_f32_32x32x16_bf16 v[32:47], v[100:103], v[2:5], v[32:47]
	v_add_u32_e32 v14, s64, v170
	v_add_u32_e32 v15, s64, v171
	s_waitcnt lgkmcnt(4)
	v_mfma_f32_32x32x16_bf16 v[32:47], v[104:107], v[6:9], v[32:47]
	s_waitcnt lgkmcnt(2)
	v_mfma_f32_32x32x16_bf16 v[32:47], v[108:111], v[10:13], v[32:47]
	s_waitcnt lgkmcnt(0)
	v_mfma_f32_32x32x16_bf16 v[32:47], v[112:115], v[96:99], v[32:47]
	ds_read_b64_tr_b16 v[100:101], v14 offset:16384
	ds_read_b64_tr_b16 v[102:103], v15 offset:16384
	ds_read_b64_tr_b16 v[104:105], v14 offset:20480
	ds_read_b64_tr_b16 v[106:107], v15 offset:20480
	ds_read_b64_tr_b16 v[108:109], v14 offset:24576
	ds_read_b64_tr_b16 v[110:111], v15 offset:24576
	ds_read_b64_tr_b16 v[112:113], v14 offset:28672
	ds_read_b64_tr_b16 v[114:115], v15 offset:28672
	s_waitcnt lgkmcnt(6)
	v_mfma_f32_32x32x16_bf16 v[16:31], v[100:103], v[2:5], v[16:31]
	s_waitcnt lgkmcnt(4)
	v_mfma_f32_32x32x16_bf16 v[16:31], v[104:107], v[6:9], v[16:31]
	s_waitcnt lgkmcnt(2)
	v_mfma_f32_32x32x16_bf16 v[16:31], v[108:111], v[10:13], v[16:31]
	s_waitcnt lgkmcnt(0)
	v_mfma_f32_32x32x16_bf16 v[16:31], v[112:115], v[96:99], v[16:31]

.LBB0_574:
	s_and_saveexec_b64 s[50:51], s[6:7]
	s_cbranch_execz .LBB0_571
	s_and_b32 s64, s11, 0x8000
	v_add_u32_e32 v175, s64, v152
	v_add_u32_e32 v176, s64, v153
	v_add_u32_e32 v177, s64, v154
	v_add_u32_e32 v178, s64, v155
	ds_read_b128 v[2:5], v175
	ds_read_b128 v[6:9], v175 offset:8192
	ds_read_b128 v[10:13], v176
	ds_read_b128 v[180:183], v176 offset:8192
	ds_read_b128 v[184:187], v177
	ds_read_b128 v[188:191], v177 offset:8192
	ds_read_b128 v[204:207], v178
	ds_read_b128 v[208:211], v178 offset:8192
	s_cmp_eq_u32 s13, 1
	s_cselect_b64 s[6:7], -1, 0
	s_cmp_lg_u32 s13, 1
	s_cselect_b64 s[54:55], -1, 0
	s_waitcnt lgkmcnt(6)
	v_mfma_f32_32x32x16_bf16 v[96:111], v[6:9], v[128:131], v[80:95]
	ds_read2_b32 v[6:7], v1 offset0:34 offset1:35
	ds_read2_b32 v[8:9], v1 offset0:40 offset1:41
	s_and_b64 vcc, exec, s[6:7]
	v_mfma_f32_32x32x16_bf16 v[112:127], v[2:5], v[128:131], v[80:95]
	ds_read2_b32 v[4:5], v1 offset0:32 offset1:33
	ds_read2_b32 v[2:3], v1 offset1:1
	s_waitcnt lgkmcnt(8)
	v_mfma_f32_32x32x16_bf16 v[96:111], v[180:183], v[132:135], v[96:111]
	v_mfma_f32_32x32x16_bf16 v[112:127], v[10:13], v[132:135], v[112:127]
	s_waitcnt lgkmcnt(6)
	v_mfma_f32_32x32x16_bf16 v[96:111], v[188:191], v[136:139], v[96:111]
	v_mfma_f32_32x32x16_bf16 v[112:127], v[184:187], v[136:139], v[112:127]
	s_waitcnt lgkmcnt(4)
	v_mfma_f32_32x32x16_bf16 v[96:111], v[208:211], v[140:143], v[96:111]
	v_mfma_f32_32x32x16_bf16 v[112:127], v[204:207], v[140:143], v[112:127]
	s_waitcnt lgkmcnt(1)
	s_nop 9
	v_add_f32_e64 v10, v96, v4
	v_add_f32_e64 v11, v97, v5
	v_add_f32_e64 v12, v98, v6
	v_add_f32_e64 v13, v99, v7
	ds_read2_b32 v[96:97], v1 offset0:42 offset1:43
	ds_read2_b32 v[98:99], v1 offset0:16 offset1:17
	ds_read2_b32 v[4:5], v1 offset0:2 offset1:3
	ds_read2_b32 v[6:7], v1 offset0:8 offset1:9
	v_pk_add_f32 v[14:15], v[100:101], v[8:9]
	ds_read2_b32 v[8:9], v1 offset0:10 offset1:11
	s_waitcnt lgkmcnt(5)
	v_pk_add_f32 v[2:3], v[112:113], v[2:3]
	s_waitcnt lgkmcnt(4)
	v_pk_add_f32 v[96:97], v[102:103], v[96:97]
	ds_read2_b32 v[100:101], v1 offset0:18 offset1:19
	ds_read2_b32 v[102:103], v1 offset0:24 offset1:25
	s_waitcnt lgkmcnt(5)
	v_pk_add_f32 v[112:113], v[120:121], v[98:99]
	ds_read2_b32 v[98:99], v1 offset0:48 offset1:49
	s_waitcnt lgkmcnt(5)
	v_pk_add_f32 v[4:5], v[114:115], v[4:5]
	s_waitcnt lgkmcnt(4)
	v_pk_add_f32 v[6:7], v[116:117], v[6:7]
	s_waitcnt lgkmcnt(2)
	v_pk_add_f32 v[114:115], v[122:123], v[100:101]
	ds_read2_b32 v[100:101], v1 offset0:50 offset1:51
	s_waitcnt lgkmcnt(2)
	v_pk_add_f32 v[116:117], v[124:125], v[102:103]
	ds_read2_b32 v[102:103], v1 offset0:56 offset1:57
	s_waitcnt lgkmcnt(2)
	v_pk_add_f32 v[98:99], v[104:105], v[98:99]
	ds_read2_b32 v[104:105], v1 offset0:26 offset1:27
	v_pk_add_f32 v[8:9], v[118:119], v[8:9]
	s_waitcnt lgkmcnt(2)
	v_pk_add_f32 v[100:101], v[106:107], v[100:101]
	s_waitcnt lgkmcnt(1)
	v_pk_add_f32 v[102:103], v[108:109], v[102:103]
	s_waitcnt lgkmcnt(0)
	v_pk_add_f32 v[118:119], v[126:127], v[104:105]
	ds_read2_b32 v[104:105], v1 offset0:58 offset1:59
	s_waitcnt lgkmcnt(0)
	v_pk_add_f32 v[104:105], v[110:111], v[104:105]
	s_cbranch_vccnz .LBB0_577
	v_exp_f32_e32 v2, v2
	v_exp_f32_e32 v10, v10
	v_exp_f32_e32 v3, v3
	v_exp_f32_e32 v11, v11
	v_add_f32_e32 v106, 0, v2
	v_exp_f32_e32 v4, v4
	v_add_f32_e32 v106, v10, v106
	v_exp_f32_e32 v12, v12
	v_add_f32_e32 v106, v106, v3
	v_exp_f32_e32 v5, v5
	v_add_f32_e32 v106, v11, v106
	v_exp_f32_e32 v13, v13
	v_add_f32_e32 v106, v106, v4
	v_exp_f32_e32 v6, v6
	v_add_f32_e32 v106, v12, v106
	v_exp_f32_e32 v14, v14
	v_add_f32_e32 v106, v106, v5
	v_exp_f32_e32 v7, v7
	v_add_f32_e32 v106, v13, v106
	v_exp_f32_e32 v15, v15
	v_add_f32_e32 v106, v106, v6
	v_exp_f32_e32 v8, v8
	v_add_f32_e32 v106, v14, v106
	v_exp_f32_e32 v96, v96
	v_add_f32_e32 v106, v106, v7
	v_exp_f32_e32 v9, v9
	v_add_f32_e32 v106, v15, v106
	v_exp_f32_e32 v97, v97
	v_add_f32_e32 v106, v106, v8
	v_exp_f32_e32 v112, v112
	v_add_f32_e32 v106, v96, v106
	v_exp_f32_e32 v98, v98
	v_add_f32_e32 v106, v106, v9
	v_exp_f32_e32 v113, v113
	v_add_f32_e32 v106, v97, v106
	v_exp_f32_e32 v99, v99
	v_add_f32_e32 v106, v106, v112
	v_exp_f32_e32 v114, v114
	v_add_f32_e32 v106, v98, v106
	v_exp_f32_e32 v100, v100
	v_add_f32_e32 v106, v106, v113
	v_exp_f32_e32 v115, v115
	v_add_f32_e32 v106, v99, v106
	v_exp_f32_e32 v101, v101
	v_add_f32_e32 v106, v106, v114
	v_exp_f32_e32 v116, v116
	v_add_f32_e32 v106, v100, v106
	v_exp_f32_e32 v102, v102
	v_add_f32_e32 v106, v106, v115
	v_exp_f32_e32 v117, v117
	v_add_f32_e32 v106, v101, v106
	v_exp_f32_e32 v103, v103
	v_add_f32_e32 v106, v106, v116
	v_exp_f32_e32 v118, v118
	v_add_f32_e32 v106, v102, v106
	v_exp_f32_e32 v104, v104
	v_add_f32_e32 v106, v106, v117
	v_exp_f32_e32 v119, v119
	v_add_f32_e32 v106, v103, v106
	v_exp_f32_e32 v105, v105
	v_add_f32_e32 v106, v106, v118
	v_add_f32_e32 v106, v104, v106
	v_add_f32_e32 v106, v106, v119
	v_add_f32_e32 v146, v105, v106
	v_cmp_nge_f32_e32 vcc, s26, v146
	s_cmp_lg_u64 vcc, 0
	s_cbranch_scc0 .LBB0_570
	s_branch .LBB0_578
